# grid barrier release flattened: non-leader workgroups poll the cross-XCD generation word directly, per-XCD release add removed
# speedup vs baseline: 1.0020x; 1.0019x over previous
.LBB0_85:
	s_or_b64 exec, exec, s[6:7]
	v_cvt_f32_u32_e32 v4, v2
	s_waitcnt vmcnt(0)
	v_readfirstlane_b32 s4, v3
	v_sub_u32_e32 v3, 0, v2
	v_rcp_iflag_f32_e32 v4, v4
	v_add_u32_e32 v5, s4, v1
	v_mul_f32_e32 v4, 0x4f7ffffe, v4
	v_cvt_u32_f32_e32 v4, v4
	v_mul_lo_u32 v1, v3, v4
	v_mul_hi_u32 v1, v4, v1
	v_add_u32_e32 v1, v4, v1
	v_mul_hi_u32 v1, v5, v1
	v_mul_lo_u32 v3, v1, v2
	v_sub_u32_e32 v3, v5, v3
	v_add_u32_e32 v4, 1, v1
	v_cmp_ge_u32_e32 vcc, v3, v2
	s_nop 1
	v_cndmask_b32_e32 v1, v1, v4, vcc
	v_sub_u32_e32 v4, v3, v2
	v_cndmask_b32_e32 v3, v3, v4, vcc
	v_add_u32_e32 v4, 1, v1
	v_cmp_ge_u32_e32 vcc, v3, v2
	v_add_u32_e32 v3, 1, v5
	s_nop 0
	v_cndmask_b32_e32 v1, v1, v4, vcc
	v_mul_lo_u32 v4, v2, v1
	v_add_u32_e32 v2, v4, v2
	v_cmp_ne_u32_e32 vcc, v3, v2
	s_and_saveexec_b64 s[4:5], vcc
	s_xor_b64 s[4:5], exec, s[4:5]
	s_cbranch_execz .LBB0_99
	s_waitcnt lgkmcnt(0)
	v_mov_b32_e32 v0, 0
	s_add_u32 s10, s70, 0xa3500
	s_addc_u32 s11, s71, 0
	global_load_dword v0, v0, s[10:11] sc1
	s_waitcnt vmcnt(0)
	v_cmp_eq_u32_e32 vcc, v0, v1
	s_and_saveexec_b64 s[6:7], vcc
	s_cbranch_execz .LBB0_98
	s_add_u32 s8, s70, 0xa0200
	s_addc_u32 s9, s71, 0
	s_mov_b32 s21, 1
	s_mov_b64 s[12:13], 0
	v_mov_b32_e32 v0, 0
	s_branch .LBB0_89

.LBB0_116:
	s_or_b64 exec, exec, s[4:5]
	s_mov_b64 s[4:5], exec
	v_mbcnt_lo_u32_b32 v0, s4, 0
	v_mbcnt_hi_u32_b32 v0, s5, v0
	v_cmp_eq_u32_e32 vcc, 0, v0
	s_waitcnt vmcnt(0)
	buffer_inv sc1
	s_and_saveexec_b64 s[6:7], vcc
	s_cbranch_execz .LBB0_118
	s_bcnt1_i32_b64 s4, s[4:5]
	v_mov_b32_e32 v0, 0x2000
	v_mov_b32_e32 v1, s4
.LBB0_118:
	s_or_b64 exec, exec, s[6:7]
	s_waitcnt vmcnt(0)

.LBB0_414:
	s_or_b64 exec, exec, s[4:5]
	s_mov_b64 s[4:5], exec
	v_mbcnt_lo_u32_b32 v0, s4, 0
	v_mbcnt_hi_u32_b32 v0, s5, v0
	v_cmp_eq_u32_e32 vcc, 0, v0
	s_waitcnt vmcnt(0)
	buffer_inv sc1
	s_and_saveexec_b64 s[6:7], vcc
	s_cbranch_execz .LBB0_416
	s_bcnt1_i32_b64 s4, s[4:5]
	v_mov_b32_e32 v0, 0x2000
	v_mov_b32_e32 v1, s4
.LBB0_416:
	s_or_b64 exec, exec, s[6:7]
	s_waitcnt vmcnt(0)

.LBB0_512:
	s_or_b64 exec, exec, s[4:5]
	s_mov_b64 s[4:5], exec
	v_mbcnt_lo_u32_b32 v0, s4, 0
	v_mbcnt_hi_u32_b32 v0, s5, v0
	v_cmp_eq_u32_e32 vcc, 0, v0
	s_waitcnt vmcnt(0)
	buffer_inv sc1
	s_and_saveexec_b64 s[6:7], vcc
	s_cbranch_execz .LBB0_514
	s_bcnt1_i32_b64 s4, s[4:5]
	v_mov_b32_e32 v0, 0x2000
	v_mov_b32_e32 v1, s4
.LBB0_514:
	s_or_b64 exec, exec, s[6:7]
	s_waitcnt vmcnt(0)

.LBB0_751:
	s_or_b64 exec, exec, s[4:5]
	s_mov_b64 s[4:5], exec
	v_mbcnt_lo_u32_b32 v0, s4, 0
	v_mbcnt_hi_u32_b32 v0, s5, v0
	v_cmp_eq_u32_e32 vcc, 0, v0
	s_waitcnt vmcnt(0)
	buffer_inv sc1
	s_and_saveexec_b64 s[6:7], vcc
	s_cbranch_execz .LBB0_753
	s_bcnt1_i32_b64 s4, s[4:5]
	v_mov_b32_e32 v0, 0x2000
	v_mov_b32_e32 v1, s4
.LBB0_753:
	s_or_b64 exec, exec, s[6:7]
	s_waitcnt vmcnt(0)

.LBB0_890:
	s_or_b64 exec, exec, s[4:5]
	s_mov_b64 s[4:5], exec
	v_mbcnt_lo_u32_b32 v0, s4, 0
	v_mbcnt_hi_u32_b32 v0, s5, v0
	v_cmp_eq_u32_e32 vcc, 0, v0
	s_waitcnt vmcnt(0)
	buffer_inv sc1
	s_and_saveexec_b64 s[6:7], vcc
	s_cbranch_execz .LBB0_892
	s_bcnt1_i32_b64 s4, s[4:5]
	v_mov_b32_e32 v0, 0x2000
	v_mov_b32_e32 v1, s4
.LBB0_892:
	s_or_b64 exec, exec, s[6:7]
	s_waitcnt vmcnt(0)

.LBB0_1016:
	s_or_b64 exec, exec, s[4:5]
	s_mov_b64 s[4:5], exec
	v_mbcnt_lo_u32_b32 v0, s4, 0
	v_mbcnt_hi_u32_b32 v0, s5, v0
	v_cmp_eq_u32_e32 vcc, 0, v0
	s_waitcnt vmcnt(0)
	buffer_inv sc1
	s_and_saveexec_b64 s[6:7], vcc
	s_cbranch_execz .LBB0_1018
	s_bcnt1_i32_b64 s4, s[4:5]
	v_mov_b32_e32 v0, 0x2000
	v_mov_b32_e32 v1, s4
.LBB0_1018:
	s_or_b64 exec, exec, s[6:7]
	s_waitcnt vmcnt(0)

.LBB0_1154:
	s_or_b64 exec, exec, s[4:5]
	s_mov_b64 s[4:5], exec
	v_mbcnt_lo_u32_b32 v0, s4, 0
	v_mbcnt_hi_u32_b32 v0, s5, v0
	v_cmp_eq_u32_e32 vcc, 0, v0
	s_waitcnt vmcnt(0)
	buffer_inv sc1
	s_and_saveexec_b64 s[6:7], vcc
	s_cbranch_execz .LBB0_1156
	s_bcnt1_i32_b64 s4, s[4:5]
	v_mov_b32_e32 v0, 0x2000
	v_mov_b32_e32 v1, s4
.LBB0_1156:
	s_or_b64 exec, exec, s[6:7]
	s_waitcnt vmcnt(0)

.LBB0_1349:
	s_or_b64 exec, exec, s[4:5]
	s_mov_b64 s[4:5], exec
	v_mbcnt_lo_u32_b32 v0, s4, 0
	v_mbcnt_hi_u32_b32 v0, s5, v0
	v_cmp_eq_u32_e32 vcc, 0, v0
	s_waitcnt vmcnt(0)
	buffer_inv sc1
	s_and_saveexec_b64 s[6:7], vcc
	s_cbranch_execz .LBB0_1351
	s_bcnt1_i32_b64 s4, s[4:5]
	v_mov_b32_e32 v0, 0x2000
	v_mov_b32_e32 v1, s4
.LBB0_1351:
	s_or_b64 exec, exec, s[6:7]
	s_waitcnt vmcnt(0)

.LBB0_1447:
	s_or_b64 exec, exec, s[4:5]
	s_mov_b64 s[4:5], exec
	v_mbcnt_lo_u32_b32 v0, s4, 0
	v_mbcnt_hi_u32_b32 v0, s5, v0
	v_cmp_eq_u32_e32 vcc, 0, v0
	s_waitcnt vmcnt(0)
	buffer_inv sc1
	s_and_saveexec_b64 s[6:7], vcc
	s_cbranch_execz .LBB0_1449
	s_bcnt1_i32_b64 s4, s[4:5]
	v_mov_b32_e32 v0, 0x2000
	v_mov_b32_e32 v1, s4
.LBB0_1449:
	s_or_b64 exec, exec, s[6:7]
	s_waitcnt vmcnt(0)

.LBB0_1686:
	s_or_b64 exec, exec, s[4:5]
	s_mov_b64 s[4:5], exec
	v_mbcnt_lo_u32_b32 v0, s4, 0
	v_mbcnt_hi_u32_b32 v0, s5, v0
	v_cmp_eq_u32_e32 vcc, 0, v0
	s_waitcnt vmcnt(0)
	buffer_inv sc1
	s_and_saveexec_b64 s[6:7], vcc
	s_cbranch_execz .LBB0_1688
	s_bcnt1_i32_b64 s4, s[4:5]
	v_mov_b32_e32 v0, 0x2000
	v_mov_b32_e32 v1, s4
.LBB0_1688:
	s_or_b64 exec, exec, s[6:7]
	s_waitcnt vmcnt(0)

.LBB0_1823:
	s_or_b64 exec, exec, s[4:5]
	s_mov_b64 s[4:5], exec
	v_mbcnt_lo_u32_b32 v0, s4, 0
	v_mbcnt_hi_u32_b32 v0, s5, v0
	v_cmp_eq_u32_e32 vcc, 0, v0
	s_waitcnt vmcnt(0)
	buffer_inv sc1
	s_and_saveexec_b64 s[6:7], vcc
	s_cbranch_execz .LBB0_1825
	s_bcnt1_i32_b64 s4, s[4:5]
	v_mov_b32_e32 v0, 0x2000
	v_mov_b32_e32 v1, s4
.LBB0_1825:
	s_or_b64 exec, exec, s[6:7]
	s_waitcnt vmcnt(0)

.LBB0_1901:
	s_or_b64 exec, exec, s[4:5]
	s_mov_b64 s[4:5], exec
	v_mbcnt_lo_u32_b32 v0, s4, 0
	v_mbcnt_hi_u32_b32 v0, s5, v0
	v_cmp_eq_u32_e32 vcc, 0, v0
	s_waitcnt vmcnt(0)
	buffer_inv sc1
	s_and_saveexec_b64 s[6:7], vcc
	s_cbranch_execz .LBB0_1903
	s_bcnt1_i32_b64 s4, s[4:5]
	v_mov_b32_e32 v0, 0x2000
	v_mov_b32_e32 v1, s4
.LBB0_1903:
	s_or_b64 exec, exec, s[6:7]
	s_waitcnt vmcnt(0)
